# skinny (sample-row) bf16 GEMM K-loops of the in/out/QKV/O projections: all loads of a trip issued first (24-32 in flight) with counted waits; plus int8 skinny deep prefetch; on top of v21
# baseline (speedup 1.0000x reference)
.LBB0_489:
	v_lshl_add_u64 v[44:45], v[34:35], 0, s[14:15]
	s_waitcnt vmcnt(2)
	v_add_co_u32_e64 v76, s[10:11], s35, v44
	v_lshl_add_u64 v[74:75], v[30:31], 0, s[14:15]
	s_nop 0
	v_addc_co_u32_e64 v77, s[10:11], 0, v45, s[10:11]
	v_add_co_u32_e64 v78, s[10:11], s36, v44
	v_lshl_add_u64 v[72:73], v[32:33], 0, s[14:15]
	s_nop 0
	v_addc_co_u32_e64 v79, s[10:11], 0, v45, s[10:11]
	s_addk_i32 s22, 0x100
	v_lshl_add_u64 v[34:35], v[34:35], 0, s[18:19]
	v_lshl_add_u64 v[30:31], v[30:31], 0, s[18:19]
	s_cmpk_gt_u32 s22, 0x1df
	v_lshl_add_u64 v[32:33], v[32:33], 0, s[18:19]
	global_load_dwordx4 v[146:149], v[74:75], off offset:-256
	global_load_dwordx4 v[154:157], v[72:73], off offset:-256
	global_load_dwordx4 v[178:181], v[72:73], off offset:-192
	global_load_dwordx4 v[182:185], v[76:77], off
	global_load_dwordx4 v[186:189], v[78:79], off
	global_load_dwordx4 v[190:193], v[76:77], off offset:64
	global_load_dwordx4 v[194:197], v[78:79], off offset:64
	global_load_dwordx4 v[198:201], v[74:75], off offset:-192
	global_load_dwordx4 v[202:205], v[74:75], off offset:-128
	global_load_dwordx4 v[206:209], v[72:73], off offset:-128
	global_load_dwordx4 v[210:213], v[72:73], off offset:-64
	global_load_dwordx4 v[216:219], v[76:77], off offset:128
	global_load_dwordx4 v[220:223], v[78:79], off offset:128
	global_load_dwordx4 v[224:227], v[76:77], off offset:192
	global_load_dwordx4 v[228:231], v[78:79], off offset:192
	global_load_dwordx4 v[236:239], v[74:75], off offset:-64
	global_load_dwordx4 v[240:243], v[74:75], off
	global_load_dwordx4 v[244:247], v[72:73], off
	global_load_dwordx4 v[248:251], v[72:73], off offset:64
	global_load_dwordx4 v[44:47], v[76:77], off offset:256
	global_load_dwordx4 v[48:51], v[78:79], off offset:256
	global_load_dwordx4 v[52:55], v[76:77], off offset:320
	global_load_dwordx4 v[56:59], v[78:79], off offset:320
	global_load_dwordx4 v[60:63], v[74:75], off offset:64
	global_load_dwordx4 v[64:67], v[74:75], off offset:128
	global_load_dwordx4 v[68:71], v[72:73], off offset:128
	global_load_dwordx4 v[80:83], v[72:73], off offset:192
	global_load_dwordx4 v[84:87], v[76:77], off offset:384
	global_load_dwordx4 v[88:91], v[78:79], off offset:384
	global_load_dwordx4 v[92:95], v[76:77], off offset:448
	global_load_dwordx4 v[96:99], v[78:79], off offset:448
	global_load_dwordx4 v[100:103], v[74:75], off offset:192
	s_waitcnt vmcnt(28)
	v_mfma_f32_16x16x32_bf16 v[14:17], v[182:185], v[154:157], v[14:17]
	s_waitcnt vmcnt(27)
	v_mfma_f32_16x16x32_bf16 v[2:5], v[186:189], v[154:157], v[2:5]
	v_mfma_f32_16x16x32_bf16 v[6:9], v[182:185], v[146:149], v[6:9]
	v_mfma_f32_16x16x32_bf16 v[10:13], v[186:189], v[146:149], v[10:13]
	s_waitcnt vmcnt(26)
	v_mfma_f32_16x16x32_bf16 v[14:17], v[190:193], v[178:181], v[14:17]
	s_waitcnt vmcnt(25)
	v_mfma_f32_16x16x32_bf16 v[2:5], v[194:197], v[178:181], v[2:5]
	s_waitcnt vmcnt(24)
	v_mfma_f32_16x16x32_bf16 v[6:9], v[190:193], v[198:201], v[6:9]
	v_mfma_f32_16x16x32_bf16 v[10:13], v[194:197], v[198:201], v[10:13]
	s_waitcnt vmcnt(20)
	v_mfma_f32_16x16x32_bf16 v[14:17], v[216:219], v[206:209], v[14:17]
	v_mfma_f32_16x16x32_bf16 v[6:9], v[216:219], v[202:205], v[6:9]
	s_waitcnt vmcnt(19)
	v_mfma_f32_16x16x32_bf16 v[2:5], v[220:223], v[206:209], v[2:5]
	v_mfma_f32_16x16x32_bf16 v[10:13], v[220:223], v[202:205], v[10:13]
	s_waitcnt vmcnt(18)
	v_mfma_f32_16x16x32_bf16 v[14:17], v[224:227], v[210:213], v[14:17]
	s_waitcnt vmcnt(17)
	v_mfma_f32_16x16x32_bf16 v[2:5], v[228:231], v[210:213], v[2:5]
	s_waitcnt vmcnt(16)
	v_mfma_f32_16x16x32_bf16 v[6:9], v[224:227], v[236:239], v[6:9]
	v_mfma_f32_16x16x32_bf16 v[10:13], v[228:231], v[236:239], v[10:13]
	s_waitcnt vmcnt(12)
	v_mfma_f32_16x16x32_bf16 v[14:17], v[44:47], v[244:247], v[14:17]
	v_mfma_f32_16x16x32_bf16 v[6:9], v[44:47], v[240:243], v[6:9]
	s_waitcnt vmcnt(11)
	v_mfma_f32_16x16x32_bf16 v[2:5], v[48:51], v[244:247], v[2:5]
	v_mfma_f32_16x16x32_bf16 v[10:13], v[48:51], v[240:243], v[10:13]
	s_waitcnt vmcnt(10)
	v_mfma_f32_16x16x32_bf16 v[14:17], v[52:55], v[248:251], v[14:17]
	s_waitcnt vmcnt(9)
	v_mfma_f32_16x16x32_bf16 v[2:5], v[56:59], v[248:251], v[2:5]
	s_waitcnt vmcnt(8)
	v_mfma_f32_16x16x32_bf16 v[6:9], v[52:55], v[60:63], v[6:9]
	v_mfma_f32_16x16x32_bf16 v[10:13], v[56:59], v[60:63], v[10:13]
	s_waitcnt vmcnt(4)
	v_mfma_f32_16x16x32_bf16 v[14:17], v[84:87], v[68:71], v[14:17]
	v_mfma_f32_16x16x32_bf16 v[6:9], v[84:87], v[64:67], v[6:9]
	s_waitcnt vmcnt(3)
	v_mfma_f32_16x16x32_bf16 v[2:5], v[88:91], v[68:71], v[2:5]
	v_mfma_f32_16x16x32_bf16 v[10:13], v[88:91], v[64:67], v[10:13]
	s_waitcnt vmcnt(2)
	v_mfma_f32_16x16x32_bf16 v[14:17], v[92:95], v[80:83], v[14:17]
	s_waitcnt vmcnt(1)
	v_mfma_f32_16x16x32_bf16 v[2:5], v[96:99], v[80:83], v[2:5]
	s_waitcnt vmcnt(0)
	v_mfma_f32_16x16x32_bf16 v[6:9], v[92:95], v[100:103], v[6:9]
	v_mfma_f32_16x16x32_bf16 v[10:13], v[96:99], v[100:103], v[10:13]
	s_cbranch_scc0 .LBB0_489
	s_nop 5
	ds_write2_b32 v41, v14, v6 offset1:16
	ds_write2_b32 v41, v15, v7 offset0:32 offset1:48
	ds_write2_b32 v41, v16, v8 offset0:64 offset1:80
	ds_write2_b32 v41, v17, v9 offset0:96 offset1:112
	v_add_u32_e32 v6, 0x800, v41
	ds_write2_b32 v6, v2, v10 offset1:16
	ds_write2_b32 v6, v3, v11 offset0:32 offset1:48
	ds_write2_b32 v6, v4, v12 offset0:64 offset1:80
	ds_write2_b32 v6, v5, v13 offset0:96 offset1:112
	s_waitcnt lgkmcnt(0)
	s_barrier
	s_and_saveexec_b64 s[22:23], vcc
	s_cbranch_execz .LBB0_505
	s_mov_b64 s[10:11], -1
	v_mov_b32_e32 v2, v1
	v_mov_b32_e32 v3, v36
	s_and_saveexec_b64 s[24:25], s[12:13]
	s_cbranch_execz .LBB0_502
	v_mov_b32_e32 v3, 0
	s_and_saveexec_b64 s[26:27], s[0:1]
	s_cbranch_execz .LBB0_496
	ds_read_b32 v2, v37
	s_mov_b32 s43, 0
	s_mov_b64 s[28:29], 0
	v_mov_b32_e32 v4, v40
	v_mov_b32_e32 v5, v37

.LBB0_679:
	v_lshl_add_u64 v[40:41], v[20:21], 0, s[14:15]
	v_add_co_u32_e32 v60, vcc, 0x69a80000, v40
	v_lshl_add_u64 v[56:57], v[18:19], 0, s[14:15]
	s_nop 0
	v_addc_co_u32_e32 v61, vcc, 0, v41, vcc
	v_add_co_u32_e32 v62, vcc, 0x69aa0000, v40
	s_addk_i32 s16, 0x100
	s_nop 0
	v_addc_co_u32_e32 v63, vcc, 0, v41, vcc
	v_lshl_add_u64 v[20:21], v[20:21], 0, s[10:11]
	s_cmpk_gt_u32 s16, 0x1df
	v_lshl_add_u64 v[18:19], v[18:19], 0, s[10:11]
	s_nop 0
	global_load_dwordx4 v[64:67], v[56:57], off offset:-256
	global_load_dwordx4 v[68:71], v[56:57], off offset:-192
	global_load_dwordx4 v[72:75], v[60:61], off
	global_load_dwordx4 v[146:149], v[60:61], off offset:64
	global_load_dwordx4 v[154:157], v[62:63], off
	global_load_dwordx4 v[178:181], v[62:63], off offset:64
	global_load_dwordx4 v[182:185], v[56:57], off offset:-128
	global_load_dwordx4 v[186:189], v[56:57], off offset:-64
	global_load_dwordx4 v[190:193], v[56:57], off
	global_load_dwordx4 v[194:197], v[60:61], off offset:128
	global_load_dwordx4 v[198:201], v[60:61], off offset:192
	global_load_dwordx4 v[202:205], v[62:63], off offset:128
	global_load_dwordx4 v[206:209], v[62:63], off offset:192
	global_load_dwordx4 v[210:213], v[56:57], off offset:64
	global_load_dwordx4 v[214:217], v[56:57], off offset:128
	global_load_dwordx4 v[218:221], v[56:57], off offset:192
	global_load_dwordx4 v[222:225], v[60:61], off offset:256
	global_load_dwordx4 v[226:229], v[60:61], off offset:320
	global_load_dwordx4 v[230:233], v[62:63], off offset:256
	global_load_dwordx4 v[236:239], v[62:63], off offset:320
	global_load_dwordx4 v[240:243], v[60:61], off offset:384
	global_load_dwordx4 v[244:247], v[62:63], off offset:384
	global_load_dwordx4 v[248:251], v[60:61], off offset:448
	global_load_dwordx4 v[28:31], v[62:63], off offset:448
	s_waitcnt vmcnt(19)
	v_mfma_f32_16x16x32_bf16 v[6:9], v[154:157], v[64:67], v[6:9]
	v_mfma_f32_16x16x32_bf16 v[2:5], v[72:75], v[64:67], v[2:5]
	v_mfma_f32_16x16x32_bf16 v[2:5], v[146:149], v[68:71], v[2:5]
	s_waitcnt vmcnt(14)
	v_mfma_f32_16x16x32_bf16 v[2:5], v[194:197], v[182:185], v[2:5]
	v_mfma_f32_16x16x32_bf16 v[6:9], v[178:181], v[68:71], v[6:9]
	s_waitcnt vmcnt(13)
	v_mfma_f32_16x16x32_bf16 v[2:5], v[198:201], v[186:189], v[2:5]
	s_waitcnt vmcnt(12)
	v_mfma_f32_16x16x32_bf16 v[6:9], v[202:205], v[182:185], v[6:9]
	s_waitcnt vmcnt(11)
	v_mfma_f32_16x16x32_bf16 v[6:9], v[206:209], v[186:189], v[6:9]
	s_waitcnt vmcnt(7)
	v_mfma_f32_16x16x32_bf16 v[2:5], v[222:225], v[190:193], v[2:5]
	s_waitcnt vmcnt(5)
	v_mfma_f32_16x16x32_bf16 v[6:9], v[230:233], v[190:193], v[6:9]
	v_mfma_f32_16x16x32_bf16 v[2:5], v[226:229], v[210:213], v[2:5]
	s_waitcnt vmcnt(4)
	v_mfma_f32_16x16x32_bf16 v[6:9], v[236:239], v[210:213], v[6:9]
	s_waitcnt vmcnt(3)
	v_mfma_f32_16x16x32_bf16 v[2:5], v[240:243], v[214:217], v[2:5]
	s_waitcnt vmcnt(2)
	v_mfma_f32_16x16x32_bf16 v[6:9], v[244:247], v[214:217], v[6:9]
	s_waitcnt vmcnt(1)
	v_mfma_f32_16x16x32_bf16 v[2:5], v[248:251], v[218:221], v[2:5]
	s_waitcnt vmcnt(0)
	v_mfma_f32_16x16x32_bf16 v[6:9], v[28:31], v[218:221], v[6:9]
	s_cbranch_scc0 .LBB0_679
	s_nop 4
	ds_write2_b32 v26, v2, v3 offset1:16
	ds_write2_b32 v26, v4, v5 offset0:32 offset1:48
	v_add_u32_e32 v2, 0x400, v26
	ds_write2_b32 v2, v6, v7 offset1:16
	ds_write2_b32 v2, v8, v9 offset0:32 offset1:48
	s_waitcnt lgkmcnt(0)
	s_barrier
	s_and_saveexec_b64 s[16:17], s[0:1]
	s_cbranch_execz .LBB0_683
	ds_read_b32 v2, v24
	s_mov_b64 s[18:19], 0
	v_mov_b32_e32 v5, v24
	v_mov_b32_e32 v4, v10

.LBB0_1273:
	v_lshl_add_u64 v[44:45], v[34:35], 0, s[28:29]
	v_add_co_u32_e32 v76, vcc, s52, v44
	v_lshl_add_u64 v[74:75], v[30:31], 0, s[28:29]
	s_nop 0
	v_addc_co_u32_e32 v77, vcc, 0, v45, vcc
	v_add_co_u32_e32 v78, vcc, s53, v44
	v_lshl_add_u64 v[72:73], v[32:33], 0, s[28:29]
	s_nop 0
	v_addc_co_u32_e32 v79, vcc, 0, v45, vcc
	s_addk_i32 s12, 0x100
	v_lshl_add_u64 v[34:35], v[34:35], 0, s[30:31]
	v_lshl_add_u64 v[30:31], v[30:31], 0, s[30:31]
	s_cmpk_gt_u32 s12, 0x1df
	v_lshl_add_u64 v[32:33], v[32:33], 0, s[30:31]
	global_load_dwordx4 v[98:101], v[74:75], off offset:-256
	global_load_dwordx4 v[110:113], v[72:73], off offset:-256
	global_load_dwordx4 v[146:149], v[72:73], off offset:-192
	global_load_dwordx4 v[154:157], v[76:77], off
	global_load_dwordx4 v[178:181], v[78:79], off
	global_load_dwordx4 v[182:185], v[76:77], off offset:64
	global_load_dwordx4 v[186:189], v[78:79], off offset:64
	global_load_dwordx4 v[190:193], v[74:75], off offset:-192
	global_load_dwordx4 v[194:197], v[74:75], off offset:-128
	global_load_dwordx4 v[198:201], v[72:73], off offset:-128
	global_load_dwordx4 v[202:205], v[72:73], off offset:-64
	global_load_dwordx4 v[206:209], v[76:77], off offset:128
	global_load_dwordx4 v[210:213], v[78:79], off offset:128
	global_load_dwordx4 v[214:217], v[76:77], off offset:192
	global_load_dwordx4 v[218:221], v[78:79], off offset:192
	global_load_dwordx4 v[222:225], v[74:75], off offset:-64
	global_load_dwordx4 v[226:229], v[74:75], off
	global_load_dwordx4 v[230:233], v[72:73], off
	global_load_dwordx4 v[236:239], v[72:73], off offset:64
	global_load_dwordx4 v[240:243], v[76:77], off offset:256
	global_load_dwordx4 v[244:247], v[78:79], off offset:256
	global_load_dwordx4 v[248:251], v[76:77], off offset:320
	global_load_dwordx4 v[44:47], v[78:79], off offset:320
	global_load_dwordx4 v[48:51], v[74:75], off offset:64
	global_load_dwordx4 v[52:55], v[74:75], off offset:128
	global_load_dwordx4 v[56:59], v[72:73], off offset:128
	global_load_dwordx4 v[60:63], v[72:73], off offset:192
	global_load_dwordx4 v[64:67], v[76:77], off offset:384
	global_load_dwordx4 v[68:71], v[78:79], off offset:384
	global_load_dwordx4 v[80:83], v[76:77], off offset:448
	global_load_dwordx4 v[84:87], v[78:79], off offset:448
	global_load_dwordx4 v[88:91], v[74:75], off offset:192
	s_waitcnt vmcnt(28)
	v_mfma_f32_16x16x32_bf16 v[14:17], v[154:157], v[110:113], v[14:17]
	s_waitcnt vmcnt(27)
	v_mfma_f32_16x16x32_bf16 v[2:5], v[178:181], v[110:113], v[2:5]
	v_mfma_f32_16x16x32_bf16 v[6:9], v[154:157], v[98:101], v[6:9]
	v_mfma_f32_16x16x32_bf16 v[10:13], v[178:181], v[98:101], v[10:13]
	s_waitcnt vmcnt(26)
	v_mfma_f32_16x16x32_bf16 v[14:17], v[182:185], v[146:149], v[14:17]
	s_waitcnt vmcnt(25)
	v_mfma_f32_16x16x32_bf16 v[2:5], v[186:189], v[146:149], v[2:5]
	s_waitcnt vmcnt(24)
	v_mfma_f32_16x16x32_bf16 v[6:9], v[182:185], v[190:193], v[6:9]
	v_mfma_f32_16x16x32_bf16 v[10:13], v[186:189], v[190:193], v[10:13]
	s_waitcnt vmcnt(20)
	v_mfma_f32_16x16x32_bf16 v[14:17], v[206:209], v[198:201], v[14:17]
	v_mfma_f32_16x16x32_bf16 v[6:9], v[206:209], v[194:197], v[6:9]
	s_waitcnt vmcnt(19)
	v_mfma_f32_16x16x32_bf16 v[2:5], v[210:213], v[198:201], v[2:5]
	v_mfma_f32_16x16x32_bf16 v[10:13], v[210:213], v[194:197], v[10:13]
	s_waitcnt vmcnt(18)
	v_mfma_f32_16x16x32_bf16 v[14:17], v[214:217], v[202:205], v[14:17]
	s_waitcnt vmcnt(17)
	v_mfma_f32_16x16x32_bf16 v[2:5], v[218:221], v[202:205], v[2:5]
	s_waitcnt vmcnt(16)
	v_mfma_f32_16x16x32_bf16 v[6:9], v[214:217], v[222:225], v[6:9]
	v_mfma_f32_16x16x32_bf16 v[10:13], v[218:221], v[222:225], v[10:13]
	s_waitcnt vmcnt(12)
	v_mfma_f32_16x16x32_bf16 v[14:17], v[240:243], v[230:233], v[14:17]
	v_mfma_f32_16x16x32_bf16 v[6:9], v[240:243], v[226:229], v[6:9]
	s_waitcnt vmcnt(11)
	v_mfma_f32_16x16x32_bf16 v[2:5], v[244:247], v[230:233], v[2:5]
	v_mfma_f32_16x16x32_bf16 v[10:13], v[244:247], v[226:229], v[10:13]
	s_waitcnt vmcnt(10)
	v_mfma_f32_16x16x32_bf16 v[14:17], v[248:251], v[236:239], v[14:17]
	s_waitcnt vmcnt(9)
	v_mfma_f32_16x16x32_bf16 v[2:5], v[44:47], v[236:239], v[2:5]
	s_waitcnt vmcnt(8)
	v_mfma_f32_16x16x32_bf16 v[6:9], v[248:251], v[48:51], v[6:9]
	v_mfma_f32_16x16x32_bf16 v[10:13], v[44:47], v[48:51], v[10:13]
	s_waitcnt vmcnt(4)
	v_mfma_f32_16x16x32_bf16 v[14:17], v[64:67], v[56:59], v[14:17]
	v_mfma_f32_16x16x32_bf16 v[6:9], v[64:67], v[52:55], v[6:9]
	s_waitcnt vmcnt(3)
	v_mfma_f32_16x16x32_bf16 v[2:5], v[68:71], v[56:59], v[2:5]
	v_mfma_f32_16x16x32_bf16 v[10:13], v[68:71], v[52:55], v[10:13]
	s_waitcnt vmcnt(2)
	v_mfma_f32_16x16x32_bf16 v[14:17], v[80:83], v[60:63], v[14:17]
	s_waitcnt vmcnt(1)
	v_mfma_f32_16x16x32_bf16 v[2:5], v[84:87], v[60:63], v[2:5]
	s_waitcnt vmcnt(0)
	v_mfma_f32_16x16x32_bf16 v[6:9], v[80:83], v[88:91], v[6:9]
	v_mfma_f32_16x16x32_bf16 v[10:13], v[84:87], v[88:91], v[10:13]
	s_cbranch_scc0 .LBB0_1273
	s_nop 5
	ds_write2_b32 v20, v14, v6 offset1:16
	ds_write2_b32 v20, v15, v7 offset0:32 offset1:48
	ds_write2_b32 v20, v16, v8 offset0:64 offset1:80
	ds_write2_b32 v20, v17, v9 offset0:96 offset1:112
	v_add_u32_e32 v6, 0x800, v20
	ds_write2_b32 v6, v2, v10 offset1:16
	ds_write2_b32 v6, v3, v11 offset0:32 offset1:48
	ds_write2_b32 v6, v4, v12 offset0:64 offset1:80
	ds_write2_b32 v6, v5, v13 offset0:96 offset1:112
	s_waitcnt lgkmcnt(0)
	s_barrier
	s_and_saveexec_b64 s[12:13], s[0:1]
	s_cbranch_execz .LBB0_1289
	s_mov_b64 s[36:37], -1
	v_mov_b32_e32 v2, v1
	v_mov_b32_e32 v3, v36
	s_and_saveexec_b64 s[34:35], s[14:15]
	s_cbranch_execz .LBB0_1286
	v_mov_b32_e32 v3, 0
	s_and_saveexec_b64 s[36:37], s[2:3]
	s_cbranch_execz .LBB0_1280
	ds_read_b32 v2, v37
	s_mov_b32 s55, 0
	s_mov_b64 s[38:39], 0
	v_mov_b32_e32 v4, v40
	v_mov_b32_e32 v5, v37

.LBB0_1540:
	v_lshl_add_u64 v[36:37], v[20:21], 0, s[10:11]
	v_add_co_u32_e32 v56, vcc, 0x69a80000, v36
	v_lshl_add_u64 v[52:53], v[18:19], 0, s[10:11]
	s_nop 0
	v_addc_co_u32_e32 v57, vcc, 0, v37, vcc
	v_add_co_u32_e32 v58, vcc, 0x69aa0000, v36
	s_addk_i32 s12, 0x100
	s_nop 0
	v_addc_co_u32_e32 v59, vcc, 0, v37, vcc
	v_lshl_add_u64 v[20:21], v[20:21], 0, s[8:9]
	s_cmpk_gt_u32 s12, 0x1df
	v_lshl_add_u64 v[18:19], v[18:19], 0, s[8:9]
	s_nop 0
	global_load_dwordx4 v[60:63], v[52:53], off offset:-256
	global_load_dwordx4 v[64:67], v[52:53], off offset:-192
	global_load_dwordx4 v[68:71], v[56:57], off
	global_load_dwordx4 v[72:75], v[56:57], off offset:64
	global_load_dwordx4 v[98:101], v[58:59], off
	global_load_dwordx4 v[110:113], v[58:59], off offset:64
	global_load_dwordx4 v[146:149], v[52:53], off offset:-128
	global_load_dwordx4 v[154:157], v[52:53], off offset:-64
	global_load_dwordx4 v[178:181], v[52:53], off
	global_load_dwordx4 v[182:185], v[56:57], off offset:128
	global_load_dwordx4 v[186:189], v[56:57], off offset:192
	global_load_dwordx4 v[190:193], v[58:59], off offset:128
	global_load_dwordx4 v[194:197], v[58:59], off offset:192
	global_load_dwordx4 v[198:201], v[52:53], off offset:64
	global_load_dwordx4 v[202:205], v[52:53], off offset:128
	global_load_dwordx4 v[206:209], v[52:53], off offset:192
	global_load_dwordx4 v[210:213], v[56:57], off offset:256
	global_load_dwordx4 v[214:217], v[56:57], off offset:320
	global_load_dwordx4 v[218:221], v[58:59], off offset:256
	global_load_dwordx4 v[222:225], v[58:59], off offset:320
	global_load_dwordx4 v[226:229], v[56:57], off offset:384
	global_load_dwordx4 v[230:233], v[58:59], off offset:384
	global_load_dwordx4 v[236:239], v[56:57], off offset:448
	global_load_dwordx4 v[240:243], v[58:59], off offset:448
	s_waitcnt vmcnt(19)
	v_mfma_f32_16x16x32_bf16 v[6:9], v[98:101], v[60:63], v[6:9]
	v_mfma_f32_16x16x32_bf16 v[2:5], v[68:71], v[60:63], v[2:5]
	v_mfma_f32_16x16x32_bf16 v[2:5], v[72:75], v[64:67], v[2:5]
	s_waitcnt vmcnt(14)
	v_mfma_f32_16x16x32_bf16 v[2:5], v[182:185], v[146:149], v[2:5]
	v_mfma_f32_16x16x32_bf16 v[6:9], v[110:113], v[64:67], v[6:9]
	s_waitcnt vmcnt(13)
	v_mfma_f32_16x16x32_bf16 v[2:5], v[186:189], v[154:157], v[2:5]
	s_waitcnt vmcnt(12)
	v_mfma_f32_16x16x32_bf16 v[6:9], v[190:193], v[146:149], v[6:9]
	s_waitcnt vmcnt(11)
	v_mfma_f32_16x16x32_bf16 v[6:9], v[194:197], v[154:157], v[6:9]
	s_waitcnt vmcnt(7)
	v_mfma_f32_16x16x32_bf16 v[2:5], v[210:213], v[178:181], v[2:5]
	s_waitcnt vmcnt(5)
	v_mfma_f32_16x16x32_bf16 v[6:9], v[218:221], v[178:181], v[6:9]
	v_mfma_f32_16x16x32_bf16 v[2:5], v[214:217], v[198:201], v[2:5]
	s_waitcnt vmcnt(4)
	v_mfma_f32_16x16x32_bf16 v[6:9], v[222:225], v[198:201], v[6:9]
	s_waitcnt vmcnt(3)
	v_mfma_f32_16x16x32_bf16 v[2:5], v[226:229], v[202:205], v[2:5]
	s_waitcnt vmcnt(2)
	v_mfma_f32_16x16x32_bf16 v[6:9], v[230:233], v[202:205], v[6:9]
	s_waitcnt vmcnt(1)
	v_mfma_f32_16x16x32_bf16 v[2:5], v[236:239], v[206:209], v[2:5]
	s_waitcnt vmcnt(0)
	v_mfma_f32_16x16x32_bf16 v[6:9], v[240:243], v[206:209], v[6:9]
	s_cbranch_scc0 .LBB0_1540
	s_nop 4
	ds_write2_b32 v23, v2, v3 offset1:16
	ds_write2_b32 v23, v4, v5 offset0:32 offset1:48
	v_add_u32_e32 v2, 0x400, v23
	ds_write2_b32 v2, v6, v7 offset1:16
	ds_write2_b32 v2, v8, v9 offset0:32 offset1:48
	s_waitcnt lgkmcnt(0)
	s_barrier
	s_and_saveexec_b64 s[12:13], s[0:1]
	s_cbranch_execz .LBB0_1544
	ds_read_b32 v2, v22
	s_mov_b64 s[14:15], 0
	v_mov_b32_e32 v5, v22
	v_mov_b32_e32 v4, v10
